# g25 + P4 compressed-attention items also distributed dynamically (atomic counter prefetched at item start, LDS broadcast at latch)
# baseline (speedup 1.0000x reference)
; DI void phase4(const Params& p, int bid, int nblk, unsigned char* smem) {
;   for (int it = bid; it < 4096; it += nblk) cmp_item(p, it, smem);
; }
.LBB0_517:
	s_or_b64 exec, exec, s[0:1]
	v_readlane_b32 s0, v245, 35
	v_mov_b32_e32 v213, 0xd000
	v_readfirstlane_b32 s98, v218
	s_cmp_lg_u32 s98, 0
	s_cbranch_scc1 .Ldyn4_skip_b
	s_waitcnt vmcnt(16)
	s_mov_b64 s[100:101], exec
	s_mov_b64 exec, 1
	ds_write_b32 v213, v210
	s_waitcnt lgkmcnt(0)
	s_mov_b64 exec, s[100:101]
.Ldyn4_skip_b:
	s_barrier
	ds_read_b32 v210, v213
	s_waitcnt lgkmcnt(0)
	v_readfirstlane_b32 s86, v210
	s_add_i32 s86, s86, s0
	s_cmpk_lt_i32 s86, 0x1000
	v_readlane_b32 s1, v245, 36
	s_cbranch_scc0 .LBB0_636
.LBB0_518:
	v_readfirstlane_b32 s98, v218
	s_cmp_lg_u32 s98, 0
	s_cbranch_scc1 .Ldyn4_skip_a
	s_mov_b64 s[100:101], exec
	s_mov_b64 exec, 1
	v_mov_b32_e32 v211, 0x3fb04080
	v_mov_b32_e32 v212, 1
	global_atomic_add v210, v211, v212, s[42:43] sc0
	s_mov_b64 exec, s[100:101]
